# fp6 up GEMM loops: DMA address math and pointer selects moved from the load segments into the preceding MFMA segments
# speedup vs baseline: 1.0195x; 1.0045x over previous
.LBB0_991:
	ds_read_b128 v[146:149], v142
	ds_read_b128 v[192:195], v142 offset:1024
	ds_read_b128 v[152:155], v142 offset:2048
	ds_read_b128 v[196:199], v142 offset:3072
	ds_read_b128 v[158:161], v143
	ds_read_b128 v[200:203], v143 offset:1024
	ds_read_b128 v[164:167], v143 offset:2048
	ds_read_b128 v[204:207], v143 offset:3072
	v_lshl_add_u64 v[150:151], s[54:55], 0, v[136:137]
	s_add_i32 m0, s29, 0xc000
	ds_read_b128 v[170:173], v144
	ds_read_b128 v[208:211], v144 offset:1024
	ds_read_b128 v[176:179], v144 offset:2048
	ds_read_b128 v[212:215], v144 offset:3072
	ds_read_b128 v[182:185], v144 offset:4096
	ds_read_b128 v[216:219], v144 offset:5120
	ds_read_b128 v[188:191], v144 offset:6144
	ds_read_b128 v[220:223], v144 offset:7168
	global_load_lds_dwordx4 v[150:151], off
	s_add_i32 m0, s29, 0xe000
	v_lshl_add_u64 v[150:151], v[150:151], 0, s[10:11]
	global_load_lds_dwordx4 v[150:151], off
	s_waitcnt vmcnt(8)
	s_waitcnt lgkmcnt(0)
	s_barrier
	s_waitcnt lgkmcnt(0)
	v_mov_b32_e32 v150, v192
	v_mov_b32_e32 v151, v193
	v_mov_b32_e32 v156, v196
	v_mov_b32_e32 v157, v197
	v_mov_b32_e32 v174, v208
	v_mov_b32_e32 v175, v209
	v_mov_b32_e32 v180, v212
	v_mov_b32_e32 v181, v213
	v_mov_b32_e32 v186, v216
	v_mov_b32_e32 v187, v217
	v_mov_b32_e32 v192, v220
	v_mov_b32_e32 v193, v221
	v_mfma_scale_f32_16x16x128_f8f6f4 v[128:131], v[146:151], v[170:175], v[128:131], v194, v210 op_sel_hi:[0,0,0] cbsz:2 blgp:2
	v_mfma_scale_f32_16x16x128_f8f6f4 v[124:127], v[152:157], v[170:175], v[124:127], v198, v210 op_sel_hi:[0,0,0] cbsz:2 blgp:2
	v_mfma_scale_f32_16x16x128_f8f6f4 v[120:123], v[146:151], v[176:181], v[120:123], v194, v214 op_sel_hi:[0,0,0] cbsz:2 blgp:2
	v_mfma_scale_f32_16x16x128_f8f6f4 v[116:119], v[152:157], v[176:181], v[116:119], v198, v214 op_sel_hi:[0,0,0] cbsz:2 blgp:2
	s_add_u32 s56, s54, 0xfffc0080
	s_addc_u32 s57, s55, -1
	s_cmp_eq_u32 s86, 12
	s_cselect_b32 s57, s4, s57
	s_cselect_b32 s56, s5, s56
	s_cselect_b32 s59, s39, s85
	s_cselect_b32 s58, s45, s84
	s_add_i32 s100, s61, s24
	s_add_i32 s101, s62, s24
	v_lshl_add_u64 v[236:237], s[58:59], 0, v[132:133]
	v_lshl_add_u64 v[240:241], v[236:237], 0, s[10:11]
	v_lshl_add_u64 v[242:243], v[236:237], 0, s[12:13]
	v_lshl_add_u64 v[238:239], s[56:57], 0, v[134:135]
	v_lshl_add_u64 v[244:245], v[236:237], 0, s[14:15]
	v_lshl_add_u64 v[246:247], v[238:239], 0, s[10:11]
	v_mfma_scale_f32_16x16x128_f8f6f4 v[112:115], v[146:151], v[182:187], v[112:115], v194, v218 op_sel_hi:[0,0,0] cbsz:2 blgp:2
	v_mfma_scale_f32_16x16x128_f8f6f4 v[108:111], v[152:157], v[182:187], v[108:111], v198, v218 op_sel_hi:[0,0,0] cbsz:2 blgp:2
	v_mfma_scale_f32_16x16x128_f8f6f4 v[104:107], v[146:151], v[188:193], v[104:107], v194, v222 op_sel_hi:[0,0,0] cbsz:2 blgp:2
	v_mfma_scale_f32_16x16x128_f8f6f4 v[100:103], v[152:157], v[188:193], v[100:103], v198, v222 op_sel_hi:[0,0,0] cbsz:2 blgp:2
	v_mov_b32_e32 v168, v204
	v_mov_b32_e32 v169, v205
	v_mov_b32_e32 v162, v200
	v_mov_b32_e32 v163, v201
	v_mfma_scale_f32_16x16x128_f8f6f4 v[30:33], v[164:169], v[188:193], v[30:33], v206, v222 op_sel_hi:[0,0,0] cbsz:2 blgp:2
	s_nop 0
	v_mfma_scale_f32_16x16x128_f8f6f4 v[224:227], v[158:163], v[170:175], v[2:5], v202, v210 op_sel_hi:[0,0,0] cbsz:2 blgp:2
	v_mfma_scale_f32_16x16x128_f8f6f4 v[170:173], v[164:169], v[170:175], v[6:9], v206, v210 op_sel_hi:[0,0,0] cbsz:2 blgp:2
	v_mfma_scale_f32_16x16x128_f8f6f4 v[208:211], v[158:163], v[176:181], v[10:13], v202, v214 op_sel_hi:[0,0,0] cbsz:2 blgp:2
	v_mfma_scale_f32_16x16x128_f8f6f4 v[174:177], v[164:169], v[176:181], v[14:17], v206, v214 op_sel_hi:[0,0,0] cbsz:2 blgp:2
	v_mfma_scale_f32_16x16x128_f8f6f4 v[178:181], v[158:163], v[182:187], v[18:21], v202, v218 op_sel_hi:[0,0,0] cbsz:2 blgp:2
	v_mfma_scale_f32_16x16x128_f8f6f4 v[182:185], v[164:169], v[182:187], v[22:25], v206, v218 op_sel_hi:[0,0,0] cbsz:2 blgp:2
	v_mfma_scale_f32_16x16x128_f8f6f4 v[212:215], v[158:163], v[188:193], v[26:29], v202, v222 op_sel_hi:[0,0,0] cbsz:2 blgp:2
	s_barrier
	s_mov_b32 m0, s100
	ds_read_b128 v[2:5], v144 offset:16384
	ds_read_b128 v[24:27], v144 offset:17408
	ds_read_b128 v[8:11], v144 offset:18432
	global_load_lds_dwordx4 v[236:237], off
	s_add_i32 m0, s100, 0x2000
	ds_read_b128 v[186:189], v144 offset:19456
	global_load_lds_dwordx4 v[240:241], off
	s_mov_b32 m0, s101
	ds_read_b128 v[14:17], v144 offset:20480
	global_load_lds_dwordx4 v[242:243], off
	s_add_i32 m0, s101, 0x2000
	ds_read_b128 v[190:193], v144 offset:21504
	global_load_lds_dwordx4 v[244:245], off
	s_mov_b32 m0, s29
	ds_read_b128 v[20:23], v144 offset:22528
	global_load_lds_dwordx4 v[238:239], off
	s_mov_b32 m0, s33
	ds_read_b128 v[216:219], v144 offset:23552
	global_load_lds_dwordx4 v[246:247], off
	s_waitcnt vmcnt(8)
	s_waitcnt lgkmcnt(0)
	s_barrier
	s_waitcnt lgkmcnt(0)
	v_mov_b32_e32 v6, v24
	v_mov_b32_e32 v7, v25
	v_mov_b32_e32 v12, v186
	v_mov_b32_e32 v13, v187
	v_mov_b32_e32 v18, v190
	v_mov_b32_e32 v19, v191
	v_mfma_scale_f32_16x16x128_f8f6f4 v[96:99], v[146:151], v[2:7], v[96:99], v194, v26 op_sel_hi:[0,0,0] cbsz:2 blgp:2
	v_mov_b32_e32 v24, v216
	v_mov_b32_e32 v25, v217
	v_mfma_scale_f32_16x16x128_f8f6f4 v[92:95], v[152:157], v[2:7], v[92:95], v198, v26 op_sel_hi:[0,0,0] cbsz:2 blgp:2
	v_mfma_scale_f32_16x16x128_f8f6f4 v[80:83], v[146:151], v[8:13], v[80:83], v194, v188 op_sel_hi:[0,0,0] cbsz:2 blgp:2
	v_mfma_scale_f32_16x16x128_f8f6f4 v[76:79], v[152:157], v[8:13], v[76:79], v198, v188 op_sel_hi:[0,0,0] cbsz:2 blgp:2
	s_add_i32 s56, 0, 0x18000
	s_add_i32 s57, 0, 0x1c000
	v_add_u32_e32 v252, 0x18000, v1
	v_add_u32_e32 v253, 0x1c000, v1
	v_lshl_add_u64 v[248:249], v[238:239], 0, s[12:13]
	v_lshl_add_u64 v[250:251], v[238:239], 0, s[14:15]
	v_mfma_scale_f32_16x16x128_f8f6f4 v[68:71], v[146:151], v[14:19], v[68:71], v194, v192 op_sel_hi:[0,0,0] cbsz:2 blgp:2
	v_mfma_scale_f32_16x16x128_f8f6f4 v[56:59], v[152:157], v[14:19], v[56:59], v198, v192 op_sel_hi:[0,0,0] cbsz:2 blgp:2
	v_mfma_scale_f32_16x16x128_f8f6f4 v[194:197], v[146:151], v[20:25], v[52:55], v194, v218 op_sel_hi:[0,0,0] cbsz:2 blgp:2
	v_mfma_scale_f32_16x16x128_f8f6f4 v[198:201], v[152:157], v[20:25], v[44:47], v198, v218 op_sel_hi:[0,0,0] cbsz:2 blgp:2
	v_mfma_scale_f32_16x16x128_f8f6f4 v[88:91], v[158:163], v[2:7], v[88:91], v202, v26 op_sel_hi:[0,0,0] cbsz:2 blgp:2
	v_mfma_scale_f32_16x16x128_f8f6f4 v[84:87], v[164:169], v[2:7], v[84:87], v206, v26 op_sel_hi:[0,0,0] cbsz:2 blgp:2
	v_mfma_scale_f32_16x16x128_f8f6f4 v[72:75], v[158:163], v[8:13], v[72:75], v202, v188 op_sel_hi:[0,0,0] cbsz:2 blgp:2
	v_mfma_scale_f32_16x16x128_f8f6f4 v[186:189], v[164:169], v[8:13], v[64:67], v206, v188 op_sel_hi:[0,0,0] cbsz:2 blgp:2
	v_mfma_scale_f32_16x16x128_f8f6f4 v[220:223], v[158:163], v[14:19], v[60:63], v202, v192 op_sel_hi:[0,0,0] cbsz:2 blgp:2
	v_mfma_scale_f32_16x16x128_f8f6f4 v[190:193], v[164:169], v[14:19], v[48:51], v206, v192 op_sel_hi:[0,0,0] cbsz:2 blgp:2
	v_mfma_scale_f32_16x16x128_f8f6f4 v[202:205], v[158:163], v[20:25], v[40:43], v202, v218 op_sel_hi:[0,0,0] cbsz:2 blgp:2
	v_mfma_scale_f32_16x16x128_f8f6f4 v[216:219], v[164:169], v[20:25], v[36:39], v206, v218 op_sel_hi:[0,0,0] cbsz:2 blgp:2
	s_barrier
	s_mov_b32 m0, s40
	ds_read_b128 v[36:39], v252
	ds_read_b128 v[52:55], v252 offset:1024
	ds_read_b128 v[42:45], v252 offset:2048
	ds_read_b128 v[64:67], v252 offset:3072
	ds_read_b128 v[146:149], v253
	ds_read_b128 v[228:231], v253 offset:1024
	ds_read_b128 v[152:155], v253 offset:2048
	ds_read_b128 v[232:235], v253 offset:3072
	ds_read_b128 v[6:9], v144 offset:32768
	ds_read_b128 v[10:13], v144 offset:33792
	ds_read_b128 v[14:17], v144 offset:34816
	ds_read_b128 v[18:21], v144 offset:35840
	ds_read_b128 v[22:25], v144 offset:36864
	ds_read_b128 v[26:29], v144 offset:37888
	global_load_lds_dwordx4 v[248:249], off
	s_mov_b32 m0, s41
	ds_read_b128 v[48:51], v144 offset:38912
	ds_read_b128 v[60:63], v144 offset:39936
	global_load_lds_dwordx4 v[250:251], off
	s_waitcnt vmcnt(8)
	s_waitcnt lgkmcnt(0)
	s_barrier
	s_waitcnt lgkmcnt(0)
	v_mov_b32_e32 v40, v52
	v_mov_b32_e32 v41, v53
	v_mov_b32_e32 v46, v64
	v_mov_b32_e32 v47, v65
	v_mov_b32_e32 v52, v60
	v_mov_b32_e32 v53, v61
	v_mfma_scale_f32_16x16x128_f8f6f4 v[128:131], v[36:41], v[6:11], v[128:131], v54, v12 op_sel_hi:[0,0,0] cbsz:2 blgp:2
	v_mfma_scale_f32_16x16x128_f8f6f4 v[124:127], v[42:47], v[6:11], v[124:127], v66, v12 op_sel_hi:[0,0,0] cbsz:2 blgp:2
	v_mfma_scale_f32_16x16x128_f8f6f4 v[120:123], v[36:41], v[14:19], v[120:123], v54, v20 op_sel_hi:[0,0,0] cbsz:2 blgp:2
	v_mfma_scale_f32_16x16x128_f8f6f4 v[116:119], v[42:47], v[14:19], v[116:119], v66, v20 op_sel_hi:[0,0,0] cbsz:2 blgp:2
	s_add_i32 s100, s56, s24
	s_add_i32 s101, s57, s24
	s_add_i32 s56, s57, s24
	v_lshl_add_u64 v[240:241], v[236:237], 0, s[22:23]
	v_lshl_add_u64 v[242:243], v[236:237], 0, s[26:27]
	v_lshl_add_u64 v[244:245], v[236:237], 0, s[30:31]
	v_lshl_add_u64 v[246:247], v[236:237], 0, s[34:35]
	v_lshl_add_u64 v[248:249], v[238:239], 0, s[22:23]
	v_lshl_add_u64 v[250:251], v[238:239], 0, s[26:27]
	v_mfma_scale_f32_16x16x128_f8f6f4 v[112:115], v[36:41], v[22:27], v[112:115], v54, v28 op_sel_hi:[0,0,0] cbsz:2 blgp:2
	v_mfma_scale_f32_16x16x128_f8f6f4 v[108:111], v[42:47], v[22:27], v[108:111], v66, v28 op_sel_hi:[0,0,0] cbsz:2 blgp:2
	v_mfma_scale_f32_16x16x128_f8f6f4 v[104:107], v[36:41], v[48:53], v[104:107], v54, v62 op_sel_hi:[0,0,0] cbsz:2 blgp:2
	v_mfma_scale_f32_16x16x128_f8f6f4 v[100:103], v[42:47], v[48:53], v[100:103], v66, v62 op_sel_hi:[0,0,0] cbsz:2 blgp:2
	v_mov_b32_e32 v150, v228
	v_mov_b32_e32 v151, v229
	v_mov_b32_e32 v156, v232
	v_mov_b32_e32 v157, v233
	v_mfma_scale_f32_16x16x128_f8f6f4 v[2:5], v[146:151], v[6:11], v[224:227], v230, v12 op_sel_hi:[0,0,0] cbsz:2 blgp:2
	s_nop 0
	v_mfma_scale_f32_16x16x128_f8f6f4 v[6:9], v[152:157], v[6:11], v[170:173], v234, v12 op_sel_hi:[0,0,0] cbsz:2 blgp:2
	v_mfma_scale_f32_16x16x128_f8f6f4 v[10:13], v[146:151], v[14:19], v[208:211], v230, v20 op_sel_hi:[0,0,0] cbsz:2 blgp:2
	v_mfma_scale_f32_16x16x128_f8f6f4 v[14:17], v[152:157], v[14:19], v[174:177], v234, v20 op_sel_hi:[0,0,0] cbsz:2 blgp:2
	v_mfma_scale_f32_16x16x128_f8f6f4 v[18:21], v[146:151], v[22:27], v[178:181], v230, v28 op_sel_hi:[0,0,0] cbsz:2 blgp:2
	v_mfma_scale_f32_16x16x128_f8f6f4 v[22:25], v[152:157], v[22:27], v[182:185], v234, v28 op_sel_hi:[0,0,0] cbsz:2 blgp:2
	v_mfma_scale_f32_16x16x128_f8f6f4 v[26:29], v[146:151], v[48:53], v[212:215], v230, v62 op_sel_hi:[0,0,0] cbsz:2 blgp:2
	v_mfma_scale_f32_16x16x128_f8f6f4 v[30:33], v[152:157], v[48:53], v[30:33], v234, v62 op_sel_hi:[0,0,0] cbsz:2 blgp:2
	s_barrier
	s_mov_b32 m0, s100
	ds_read_b128 v[60:63], v144 offset:49152
	ds_read_b128 v[48:51], v144 offset:50176
	ds_read_b128 v[158:161], v144 offset:51200
	global_load_lds_dwordx4 v[240:241], off
	s_add_i32 m0, s100, 0x2000
	ds_read_b128 v[174:177], v144 offset:52224
	global_load_lds_dwordx4 v[242:243], off
	s_mov_b32 m0, s101
	ds_read_b128 v[164:167], v144 offset:53248
	global_load_lds_dwordx4 v[244:245], off
	s_add_i32 m0, s101, 0x2000
	ds_read_b128 v[178:181], v144 offset:54272
	global_load_lds_dwordx4 v[246:247], off
	s_mov_b32 m0, s43
	ds_read_b128 v[170:173], v144 offset:55296
	global_load_lds_dwordx4 v[248:249], off
	s_mov_b32 m0, s50
	ds_read_b128 v[182:185], v144 offset:56320
	global_load_lds_dwordx4 v[250:251], off
	s_waitcnt vmcnt(8)
	s_waitcnt lgkmcnt(0)
	s_barrier
	s_waitcnt lgkmcnt(0)
	v_mov_b32_e32 v64, v48
	v_mov_b32_e32 v65, v49
	v_mov_b32_e32 v162, v174
	v_mov_b32_e32 v163, v175
	v_mov_b32_e32 v168, v178
	v_mov_b32_e32 v169, v179
	v_mov_b32_e32 v174, v182
	v_mov_b32_e32 v175, v183
	v_mfma_scale_f32_16x16x128_f8f6f4 v[96:99], v[36:41], v[60:65], v[96:99], v54, v50 op_sel_hi:[0,0,0] cbsz:2 blgp:2
	v_mfma_scale_f32_16x16x128_f8f6f4 v[92:95], v[42:47], v[60:65], v[92:95], v66, v50 op_sel_hi:[0,0,0] cbsz:2 blgp:2
	v_mfma_scale_f32_16x16x128_f8f6f4 v[80:83], v[36:41], v[158:163], v[80:83], v54, v176 op_sel_hi:[0,0,0] cbsz:2 blgp:2
	v_mfma_scale_f32_16x16x128_f8f6f4 v[76:79], v[42:47], v[158:163], v[76:79], v66, v176 op_sel_hi:[0,0,0] cbsz:2 blgp:2
	v_mfma_scale_f32_16x16x128_f8f6f4 v[68:71], v[36:41], v[164:169], v[68:71], v54, v180 op_sel_hi:[0,0,0] cbsz:2 blgp:2
	v_mfma_scale_f32_16x16x128_f8f6f4 v[56:59], v[42:47], v[164:169], v[56:59], v66, v180 op_sel_hi:[0,0,0] cbsz:2 blgp:2
	v_mfma_scale_f32_16x16x128_f8f6f4 v[52:55], v[36:41], v[170:175], v[194:197], v54, v184 op_sel_hi:[0,0,0] cbsz:2 blgp:2
	v_mfma_scale_f32_16x16x128_f8f6f4 v[44:47], v[42:47], v[170:175], v[198:201], v66, v184 op_sel_hi:[0,0,0] cbsz:2 blgp:2
	v_mfma_scale_f32_16x16x128_f8f6f4 v[88:91], v[146:151], v[60:65], v[88:91], v230, v50 op_sel_hi:[0,0,0] cbsz:2 blgp:2
	v_mfma_scale_f32_16x16x128_f8f6f4 v[84:87], v[152:157], v[60:65], v[84:87], v234, v50 op_sel_hi:[0,0,0] cbsz:2 blgp:2
	v_mfma_scale_f32_16x16x128_f8f6f4 v[72:75], v[146:151], v[158:163], v[72:75], v230, v176 op_sel_hi:[0,0,0] cbsz:2 blgp:2
	v_mfma_scale_f32_16x16x128_f8f6f4 v[64:67], v[152:157], v[158:163], v[186:189], v234, v176 op_sel_hi:[0,0,0] cbsz:2 blgp:2
	v_mfma_scale_f32_16x16x128_f8f6f4 v[60:63], v[146:151], v[164:169], v[220:223], v230, v180 op_sel_hi:[0,0,0] cbsz:2 blgp:2
	v_mfma_scale_f32_16x16x128_f8f6f4 v[48:51], v[152:157], v[164:169], v[190:193], v234, v180 op_sel_hi:[0,0,0] cbsz:2 blgp:2
	v_mfma_scale_f32_16x16x128_f8f6f4 v[40:43], v[146:151], v[170:175], v[202:205], v230, v184 op_sel_hi:[0,0,0] cbsz:2 blgp:2
	v_mfma_scale_f32_16x16x128_f8f6f4 v[36:39], v[152:157], v[170:175], v[216:219], v234, v184 op_sel_hi:[0,0,0] cbsz:2 blgp:2
	s_barrier
	s_add_i32 s86, s86, 2
	s_add_u32 s54, s54, 0x100
	s_addc_u32 s55, s55, 0
	s_add_u32 s84, s84, 0x100
	s_addc_u32 s85, s85, 0
	s_cmp_gt_u32 s86, 13
	s_cbranch_scc0 .LBB0_991
	s_setprio 0
	s_and_b64 vcc, exec, s[36:37]
	s_cbranch_vccz .LBB0_994
	s_barrier

.LBB0_2187:
	ds_read_b128 v[142:145], v138
	ds_read_b128 v[188:191], v138 offset:1024
	ds_read_b128 v[148:151], v138 offset:2048
	ds_read_b128 v[192:195], v138 offset:3072
	ds_read_b128 v[154:157], v139
	ds_read_b128 v[196:199], v139 offset:1024
	ds_read_b128 v[160:163], v139 offset:2048
	ds_read_b128 v[200:203], v139 offset:3072
	v_lshl_add_u64 v[146:147], s[48:49], 0, v[136:137]
	s_add_i32 m0, s33, 0xc000
	ds_read_b128 v[166:169], v140
	ds_read_b128 v[204:207], v140 offset:1024
	ds_read_b128 v[172:175], v140 offset:2048
	ds_read_b128 v[208:211], v140 offset:3072
	ds_read_b128 v[178:181], v140 offset:4096
	ds_read_b128 v[212:215], v140 offset:5120
	ds_read_b128 v[184:187], v140 offset:6144
	ds_read_b128 v[216:219], v140 offset:7168
	global_load_lds_dwordx4 v[146:147], off
	s_add_i32 m0, s33, 0xe000
	v_lshl_add_u64 v[146:147], v[146:147], 0, s[6:7]
	global_load_lds_dwordx4 v[146:147], off
	s_waitcnt vmcnt(8)
	s_waitcnt lgkmcnt(0)
	s_barrier
	s_waitcnt lgkmcnt(0)
	v_mov_b32_e32 v146, v188
	v_mov_b32_e32 v147, v189
	v_mov_b32_e32 v152, v192
	v_mov_b32_e32 v153, v193
	v_mov_b32_e32 v170, v204
	v_mov_b32_e32 v171, v205
	v_mov_b32_e32 v176, v208
	v_mov_b32_e32 v177, v209
	v_mov_b32_e32 v182, v212
	v_mov_b32_e32 v183, v213
	v_mov_b32_e32 v188, v216
	v_mov_b32_e32 v189, v217
	v_mfma_scale_f32_16x16x128_f8f6f4 v[128:131], v[142:147], v[166:171], v[128:131], v190, v206 op_sel_hi:[0,0,0] cbsz:2 blgp:2
	v_mfma_scale_f32_16x16x128_f8f6f4 v[124:127], v[148:153], v[166:171], v[124:127], v194, v206 op_sel_hi:[0,0,0] cbsz:2 blgp:2
	v_mfma_scale_f32_16x16x128_f8f6f4 v[120:123], v[142:147], v[172:177], v[120:123], v190, v210 op_sel_hi:[0,0,0] cbsz:2 blgp:2
	v_mfma_scale_f32_16x16x128_f8f6f4 v[116:119], v[148:153], v[172:177], v[116:119], v194, v210 op_sel_hi:[0,0,0] cbsz:2 blgp:2
	s_add_u32 s50, s48, 0xfffc0080
	s_addc_u32 s51, s49, -1
	s_cmp_eq_u32 s76, 12
	s_cselect_b32 s51, s35, s51
	s_cselect_b32 s50, s47, s50
	s_cselect_b32 s53, s37, s67
	s_cselect_b32 s52, s65, s66
	s_add_i32 s100, s57, s29
	s_add_i32 s101, s58, s29
	v_lshl_add_u64 v[232:233], s[52:53], 0, v[132:133]
	v_lshl_add_u64 v[240:241], v[232:233], 0, s[6:7]
	v_lshl_add_u64 v[242:243], v[232:233], 0, s[8:9]
	v_lshl_add_u64 v[234:235], s[50:51], 0, v[134:135]
	v_lshl_add_u64 v[244:245], v[232:233], 0, s[10:11]
	v_lshl_add_u64 v[246:247], v[234:235], 0, s[6:7]
	v_mfma_scale_f32_16x16x128_f8f6f4 v[112:115], v[142:147], v[178:183], v[112:115], v190, v214 op_sel_hi:[0,0,0] cbsz:2 blgp:2
	v_mfma_scale_f32_16x16x128_f8f6f4 v[108:111], v[148:153], v[178:183], v[108:111], v194, v214 op_sel_hi:[0,0,0] cbsz:2 blgp:2
	v_mfma_scale_f32_16x16x128_f8f6f4 v[104:107], v[142:147], v[184:189], v[104:107], v190, v218 op_sel_hi:[0,0,0] cbsz:2 blgp:2
	v_mfma_scale_f32_16x16x128_f8f6f4 v[100:103], v[148:153], v[184:189], v[100:103], v194, v218 op_sel_hi:[0,0,0] cbsz:2 blgp:2
	v_mov_b32_e32 v164, v200
	v_mov_b32_e32 v165, v201
	v_mov_b32_e32 v158, v196
	v_mov_b32_e32 v159, v197
	v_mfma_scale_f32_16x16x128_f8f6f4 v[30:33], v[160:165], v[184:189], v[30:33], v202, v218 op_sel_hi:[0,0,0] cbsz:2 blgp:2
	s_nop 0
	v_mfma_scale_f32_16x16x128_f8f6f4 v[220:223], v[154:159], v[166:171], v[2:5], v198, v206 op_sel_hi:[0,0,0] cbsz:2 blgp:2
	v_mfma_scale_f32_16x16x128_f8f6f4 v[166:169], v[160:165], v[166:171], v[6:9], v202, v206 op_sel_hi:[0,0,0] cbsz:2 blgp:2
	v_mfma_scale_f32_16x16x128_f8f6f4 v[204:207], v[154:159], v[172:177], v[10:13], v198, v210 op_sel_hi:[0,0,0] cbsz:2 blgp:2
	v_mfma_scale_f32_16x16x128_f8f6f4 v[170:173], v[160:165], v[172:177], v[14:17], v202, v210 op_sel_hi:[0,0,0] cbsz:2 blgp:2
	v_mfma_scale_f32_16x16x128_f8f6f4 v[174:177], v[154:159], v[178:183], v[18:21], v198, v214 op_sel_hi:[0,0,0] cbsz:2 blgp:2
	v_mfma_scale_f32_16x16x128_f8f6f4 v[178:181], v[160:165], v[178:183], v[22:25], v202, v214 op_sel_hi:[0,0,0] cbsz:2 blgp:2
	v_mfma_scale_f32_16x16x128_f8f6f4 v[208:211], v[154:159], v[184:189], v[26:29], v198, v218 op_sel_hi:[0,0,0] cbsz:2 blgp:2
	s_barrier
	s_mov_b32 m0, s100
	ds_read_b128 v[2:5], v140 offset:16384
	ds_read_b128 v[24:27], v140 offset:17408
	ds_read_b128 v[8:11], v140 offset:18432
	global_load_lds_dwordx4 v[232:233], off
	s_add_i32 m0, s100, 0x2000
	ds_read_b128 v[182:185], v140 offset:19456
	global_load_lds_dwordx4 v[240:241], off
	s_mov_b32 m0, s101
	ds_read_b128 v[14:17], v140 offset:20480
	global_load_lds_dwordx4 v[242:243], off
	s_add_i32 m0, s101, 0x2000
	ds_read_b128 v[186:189], v140 offset:21504
	global_load_lds_dwordx4 v[244:245], off
	s_mov_b32 m0, s33
	ds_read_b128 v[20:23], v140 offset:22528
	global_load_lds_dwordx4 v[234:235], off
	s_mov_b32 m0, s40
	ds_read_b128 v[212:215], v140 offset:23552
	global_load_lds_dwordx4 v[246:247], off
	s_waitcnt vmcnt(8)
	s_waitcnt lgkmcnt(0)
	s_barrier
	s_waitcnt lgkmcnt(0)
	v_mov_b32_e32 v6, v24
	v_mov_b32_e32 v7, v25
	v_mov_b32_e32 v12, v182
	v_mov_b32_e32 v13, v183
	v_mov_b32_e32 v18, v186
	v_mov_b32_e32 v19, v187
	v_mfma_scale_f32_16x16x128_f8f6f4 v[96:99], v[142:147], v[2:7], v[96:99], v190, v26 op_sel_hi:[0,0,0] cbsz:2 blgp:2
	v_mov_b32_e32 v24, v212
	v_mov_b32_e32 v25, v213
	v_mfma_scale_f32_16x16x128_f8f6f4 v[92:95], v[148:153], v[2:7], v[92:95], v194, v26 op_sel_hi:[0,0,0] cbsz:2 blgp:2
	v_mfma_scale_f32_16x16x128_f8f6f4 v[80:83], v[142:147], v[8:13], v[80:83], v190, v184 op_sel_hi:[0,0,0] cbsz:2 blgp:2
	v_mfma_scale_f32_16x16x128_f8f6f4 v[76:79], v[148:153], v[8:13], v[76:79], v194, v184 op_sel_hi:[0,0,0] cbsz:2 blgp:2
	s_add_i32 s50, 0, 0x18000
	s_add_i32 s51, 0, 0x1c000
	v_add_u32_e32 v252, 0x18000, v1
	v_add_u32_e32 v253, 0x1c000, v1
	v_lshl_add_u64 v[248:249], v[234:235], 0, s[8:9]
	v_lshl_add_u64 v[250:251], v[234:235], 0, s[10:11]
	v_mfma_scale_f32_16x16x128_f8f6f4 v[68:71], v[142:147], v[14:19], v[68:71], v190, v188 op_sel_hi:[0,0,0] cbsz:2 blgp:2
	v_mfma_scale_f32_16x16x128_f8f6f4 v[56:59], v[148:153], v[14:19], v[56:59], v194, v188 op_sel_hi:[0,0,0] cbsz:2 blgp:2
	v_mfma_scale_f32_16x16x128_f8f6f4 v[190:193], v[142:147], v[20:25], v[52:55], v190, v214 op_sel_hi:[0,0,0] cbsz:2 blgp:2
	v_mfma_scale_f32_16x16x128_f8f6f4 v[194:197], v[148:153], v[20:25], v[44:47], v194, v214 op_sel_hi:[0,0,0] cbsz:2 blgp:2
	v_mfma_scale_f32_16x16x128_f8f6f4 v[88:91], v[154:159], v[2:7], v[88:91], v198, v26 op_sel_hi:[0,0,0] cbsz:2 blgp:2
	v_mfma_scale_f32_16x16x128_f8f6f4 v[84:87], v[160:165], v[2:7], v[84:87], v202, v26 op_sel_hi:[0,0,0] cbsz:2 blgp:2
	v_mfma_scale_f32_16x16x128_f8f6f4 v[72:75], v[154:159], v[8:13], v[72:75], v198, v184 op_sel_hi:[0,0,0] cbsz:2 blgp:2
	v_mfma_scale_f32_16x16x128_f8f6f4 v[182:185], v[160:165], v[8:13], v[64:67], v202, v184 op_sel_hi:[0,0,0] cbsz:2 blgp:2
	v_mfma_scale_f32_16x16x128_f8f6f4 v[216:219], v[154:159], v[14:19], v[60:63], v198, v188 op_sel_hi:[0,0,0] cbsz:2 blgp:2
	v_mfma_scale_f32_16x16x128_f8f6f4 v[186:189], v[160:165], v[14:19], v[48:51], v202, v188 op_sel_hi:[0,0,0] cbsz:2 blgp:2
	v_mfma_scale_f32_16x16x128_f8f6f4 v[198:201], v[154:159], v[20:25], v[40:43], v198, v214 op_sel_hi:[0,0,0] cbsz:2 blgp:2
	v_mfma_scale_f32_16x16x128_f8f6f4 v[212:215], v[160:165], v[20:25], v[36:39], v202, v214 op_sel_hi:[0,0,0] cbsz:2 blgp:2
	s_barrier
	s_mov_b32 m0, s41
	ds_read_b128 v[36:39], v252
	ds_read_b128 v[52:55], v252 offset:1024
	ds_read_b128 v[42:45], v252 offset:2048
	ds_read_b128 v[64:67], v252 offset:3072
	ds_read_b128 v[142:145], v253
	ds_read_b128 v[224:227], v253 offset:1024
	ds_read_b128 v[148:151], v253 offset:2048
	ds_read_b128 v[228:231], v253 offset:3072
	ds_read_b128 v[6:9], v140 offset:32768
	ds_read_b128 v[10:13], v140 offset:33792
	ds_read_b128 v[14:17], v140 offset:34816
	ds_read_b128 v[18:21], v140 offset:35840
	ds_read_b128 v[22:25], v140 offset:36864
	ds_read_b128 v[26:29], v140 offset:37888
	global_load_lds_dwordx4 v[248:249], off
	s_mov_b32 m0, s42
	ds_read_b128 v[48:51], v140 offset:38912
	ds_read_b128 v[60:63], v140 offset:39936
	global_load_lds_dwordx4 v[250:251], off
	s_waitcnt vmcnt(8)
	s_waitcnt lgkmcnt(0)
	s_barrier
	s_waitcnt lgkmcnt(0)
	v_mov_b32_e32 v40, v52
	v_mov_b32_e32 v41, v53
	v_mov_b32_e32 v46, v64
	v_mov_b32_e32 v47, v65
	v_mov_b32_e32 v52, v60
	v_mov_b32_e32 v53, v61
	v_mfma_scale_f32_16x16x128_f8f6f4 v[128:131], v[36:41], v[6:11], v[128:131], v54, v12 op_sel_hi:[0,0,0] cbsz:2 blgp:2
	v_mfma_scale_f32_16x16x128_f8f6f4 v[124:127], v[42:47], v[6:11], v[124:127], v66, v12 op_sel_hi:[0,0,0] cbsz:2 blgp:2
	v_mfma_scale_f32_16x16x128_f8f6f4 v[120:123], v[36:41], v[14:19], v[120:123], v54, v20 op_sel_hi:[0,0,0] cbsz:2 blgp:2
	v_mfma_scale_f32_16x16x128_f8f6f4 v[116:119], v[42:47], v[14:19], v[116:119], v66, v20 op_sel_hi:[0,0,0] cbsz:2 blgp:2
	s_add_i32 s100, s50, s29
	s_add_i32 s101, s51, s29
	s_add_i32 s50, s51, s29
	v_lshl_add_u64 v[240:241], v[232:233], 0, s[20:21]
	v_lshl_add_u64 v[242:243], v[232:233], 0, s[22:23]
	v_lshl_add_u64 v[244:245], v[232:233], 0, s[24:25]
	v_lshl_add_u64 v[246:247], v[232:233], 0, s[26:27]
	v_lshl_add_u64 v[248:249], v[234:235], 0, s[20:21]
	v_lshl_add_u64 v[250:251], v[234:235], 0, s[22:23]
	v_mfma_scale_f32_16x16x128_f8f6f4 v[112:115], v[36:41], v[22:27], v[112:115], v54, v28 op_sel_hi:[0,0,0] cbsz:2 blgp:2
	v_mfma_scale_f32_16x16x128_f8f6f4 v[108:111], v[42:47], v[22:27], v[108:111], v66, v28 op_sel_hi:[0,0,0] cbsz:2 blgp:2
	v_mfma_scale_f32_16x16x128_f8f6f4 v[104:107], v[36:41], v[48:53], v[104:107], v54, v62 op_sel_hi:[0,0,0] cbsz:2 blgp:2
	v_mfma_scale_f32_16x16x128_f8f6f4 v[100:103], v[42:47], v[48:53], v[100:103], v66, v62 op_sel_hi:[0,0,0] cbsz:2 blgp:2
	v_mov_b32_e32 v146, v224
	v_mov_b32_e32 v147, v225
	v_mov_b32_e32 v152, v228
	v_mov_b32_e32 v153, v229
	v_mfma_scale_f32_16x16x128_f8f6f4 v[2:5], v[142:147], v[6:11], v[220:223], v226, v12 op_sel_hi:[0,0,0] cbsz:2 blgp:2
	s_nop 0
	v_mfma_scale_f32_16x16x128_f8f6f4 v[6:9], v[148:153], v[6:11], v[166:169], v230, v12 op_sel_hi:[0,0,0] cbsz:2 blgp:2
	v_mfma_scale_f32_16x16x128_f8f6f4 v[10:13], v[142:147], v[14:19], v[204:207], v226, v20 op_sel_hi:[0,0,0] cbsz:2 blgp:2
	v_mfma_scale_f32_16x16x128_f8f6f4 v[14:17], v[148:153], v[14:19], v[170:173], v230, v20 op_sel_hi:[0,0,0] cbsz:2 blgp:2
	v_mfma_scale_f32_16x16x128_f8f6f4 v[18:21], v[142:147], v[22:27], v[174:177], v226, v28 op_sel_hi:[0,0,0] cbsz:2 blgp:2
	v_mfma_scale_f32_16x16x128_f8f6f4 v[22:25], v[148:153], v[22:27], v[178:181], v230, v28 op_sel_hi:[0,0,0] cbsz:2 blgp:2
	v_mfma_scale_f32_16x16x128_f8f6f4 v[26:29], v[142:147], v[48:53], v[208:211], v226, v62 op_sel_hi:[0,0,0] cbsz:2 blgp:2
	v_mfma_scale_f32_16x16x128_f8f6f4 v[30:33], v[148:153], v[48:53], v[30:33], v230, v62 op_sel_hi:[0,0,0] cbsz:2 blgp:2
	s_barrier
	s_mov_b32 m0, s100
	ds_read_b128 v[60:63], v140 offset:49152
	ds_read_b128 v[48:51], v140 offset:50176
	ds_read_b128 v[154:157], v140 offset:51200
	global_load_lds_dwordx4 v[240:241], off
	s_add_i32 m0, s100, 0x2000
	ds_read_b128 v[170:173], v140 offset:52224
	global_load_lds_dwordx4 v[242:243], off
	s_mov_b32 m0, s101
	ds_read_b128 v[160:163], v140 offset:53248
	global_load_lds_dwordx4 v[244:245], off
	s_add_i32 m0, s101, 0x2000
	ds_read_b128 v[174:177], v140 offset:54272
	global_load_lds_dwordx4 v[246:247], off
	s_mov_b32 m0, s43
	ds_read_b128 v[166:169], v140 offset:55296
	global_load_lds_dwordx4 v[248:249], off
	s_mov_b32 m0, s54
	ds_read_b128 v[178:181], v140 offset:56320
	global_load_lds_dwordx4 v[250:251], off
	s_waitcnt vmcnt(8)
	s_waitcnt lgkmcnt(0)
	s_barrier
	s_waitcnt lgkmcnt(0)
	v_mov_b32_e32 v64, v48
	v_mov_b32_e32 v65, v49
	v_mov_b32_e32 v158, v170
	v_mov_b32_e32 v159, v171
	v_mov_b32_e32 v164, v174
	v_mov_b32_e32 v165, v175
	v_mov_b32_e32 v170, v178
	v_mov_b32_e32 v171, v179
	v_mfma_scale_f32_16x16x128_f8f6f4 v[96:99], v[36:41], v[60:65], v[96:99], v54, v50 op_sel_hi:[0,0,0] cbsz:2 blgp:2
	v_mfma_scale_f32_16x16x128_f8f6f4 v[92:95], v[42:47], v[60:65], v[92:95], v66, v50 op_sel_hi:[0,0,0] cbsz:2 blgp:2
	v_mfma_scale_f32_16x16x128_f8f6f4 v[80:83], v[36:41], v[154:159], v[80:83], v54, v172 op_sel_hi:[0,0,0] cbsz:2 blgp:2
	v_mfma_scale_f32_16x16x128_f8f6f4 v[76:79], v[42:47], v[154:159], v[76:79], v66, v172 op_sel_hi:[0,0,0] cbsz:2 blgp:2
	v_mfma_scale_f32_16x16x128_f8f6f4 v[68:71], v[36:41], v[160:165], v[68:71], v54, v176 op_sel_hi:[0,0,0] cbsz:2 blgp:2
	v_mfma_scale_f32_16x16x128_f8f6f4 v[56:59], v[42:47], v[160:165], v[56:59], v66, v176 op_sel_hi:[0,0,0] cbsz:2 blgp:2
	v_mfma_scale_f32_16x16x128_f8f6f4 v[52:55], v[36:41], v[166:171], v[190:193], v54, v180 op_sel_hi:[0,0,0] cbsz:2 blgp:2
	v_mfma_scale_f32_16x16x128_f8f6f4 v[44:47], v[42:47], v[166:171], v[194:197], v66, v180 op_sel_hi:[0,0,0] cbsz:2 blgp:2
	v_mfma_scale_f32_16x16x128_f8f6f4 v[88:91], v[142:147], v[60:65], v[88:91], v226, v50 op_sel_hi:[0,0,0] cbsz:2 blgp:2
	v_mfma_scale_f32_16x16x128_f8f6f4 v[84:87], v[148:153], v[60:65], v[84:87], v230, v50 op_sel_hi:[0,0,0] cbsz:2 blgp:2
	v_mfma_scale_f32_16x16x128_f8f6f4 v[72:75], v[142:147], v[154:159], v[72:75], v226, v172 op_sel_hi:[0,0,0] cbsz:2 blgp:2
	v_mfma_scale_f32_16x16x128_f8f6f4 v[64:67], v[148:153], v[154:159], v[182:185], v230, v172 op_sel_hi:[0,0,0] cbsz:2 blgp:2
	v_mfma_scale_f32_16x16x128_f8f6f4 v[60:63], v[142:147], v[160:165], v[216:219], v226, v176 op_sel_hi:[0,0,0] cbsz:2 blgp:2
	v_mfma_scale_f32_16x16x128_f8f6f4 v[48:51], v[148:153], v[160:165], v[186:189], v230, v176 op_sel_hi:[0,0,0] cbsz:2 blgp:2
	v_mfma_scale_f32_16x16x128_f8f6f4 v[40:43], v[142:147], v[166:171], v[198:201], v226, v180 op_sel_hi:[0,0,0] cbsz:2 blgp:2
	v_mfma_scale_f32_16x16x128_f8f6f4 v[36:39], v[148:153], v[166:171], v[212:215], v230, v180 op_sel_hi:[0,0,0] cbsz:2 blgp:2
	s_barrier
	s_add_i32 s76, s76, 2
	s_add_u32 s48, s48, 0x100
	s_addc_u32 s49, s49, 0
	s_add_u32 s66, s66, 0x100
	s_addc_u32 s67, s67, 0
	s_cmp_gt_u32 s76, 13
	s_cbranch_scc0 .LBB0_2187
	s_setprio 0
	s_and_b64 vcc, exec, s[30:31]
	s_cbranch_vccz .LBB0_2190
	s_barrier

	.amdhsa_kernel _Z3fwd4Args
		.amdhsa_group_segment_fixed_size 0
		.amdhsa_private_segment_fixed_size 0
		.amdhsa_kernarg_size 448
		.amdhsa_user_sgpr_count 2
		.amdhsa_user_sgpr_dispatch_ptr 0
		.amdhsa_user_sgpr_queue_ptr 0
		.amdhsa_user_sgpr_kernarg_segment_ptr 1
		.amdhsa_user_sgpr_dispatch_id 0
		.amdhsa_user_sgpr_kernarg_preload_length 0
		.amdhsa_user_sgpr_kernarg_preload_offset 0
		.amdhsa_user_sgpr_private_segment_size 0
		.amdhsa_uses_dynamic_stack 0
		.amdhsa_enable_private_segment 0
		.amdhsa_system_sgpr_workgroup_id_x 1
		.amdhsa_system_sgpr_workgroup_id_y 0
		.amdhsa_system_sgpr_workgroup_id_z 0
		.amdhsa_system_sgpr_workgroup_info 0
		.amdhsa_system_vgpr_workitem_id 0
		.amdhsa_next_free_vgpr 255
		.amdhsa_next_free_sgpr 102
		.amdhsa_accum_offset 256
		.amdhsa_reserve_vcc 1
		.amdhsa_float_round_mode_32 0
		.amdhsa_float_round_mode_16_64 0
		.amdhsa_float_denorm_mode_32 3
		.amdhsa_float_denorm_mode_16_64 3
		.amdhsa_dx10_clamp 1
		.amdhsa_ieee_mode 1
		.amdhsa_fp16_overflow 0
		.amdhsa_tg_split 0
		.amdhsa_exception_fp_ieee_invalid_op 0
		.amdhsa_exception_fp_denorm_src 0
		.amdhsa_exception_fp_ieee_div_zero 0
		.amdhsa_exception_fp_ieee_overflow 0
		.amdhsa_exception_fp_ieee_underflow 0
		.amdhsa_exception_fp_ieee_inexact 0
		.amdhsa_exception_int_div_zero 0
	.end_amdhsa_kernel

.Lfunc_end0:
	.size	_Z3fwd4Args, .Lfunc_end0-_Z3fwd4Args
	.set _Z3fwd4Args.num_vgpr, 255
	.set _Z3fwd4Args.num_agpr, 0
	.set _Z3fwd4Args.numbered_sgpr, 102
	.set _Z3fwd4Args.num_named_barrier, 0
	.set _Z3fwd4Args.private_seg_size, 0
	.set _Z3fwd4Args.uses_vcc, 1
	.set _Z3fwd4Args.uses_flat_scratch, 0
	.set _Z3fwd4Args.has_dyn_sized_stack, 0
	.set _Z3fwd4Args.has_recursion, 0
	.set _Z3fwd4Args.has_indirect_call, 0

amdhsa.kernels:
  - .agpr_count:     0
    .args:
      - .offset:         0
        .size:           192
        .value_kind:     by_value
      - .offset:         192
        .size:           4
        .value_kind:     hidden_block_count_x
      - .offset:         196
        .size:           4
        .value_kind:     hidden_block_count_y
      - .offset:         200
        .size:           4
        .value_kind:     hidden_block_count_z
      - .offset:         204
        .size:           2
        .value_kind:     hidden_group_size_x
      - .offset:         206
        .size:           2
        .value_kind:     hidden_group_size_y
      - .offset:         208
        .size:           2
        .value_kind:     hidden_group_size_z
      - .offset:         210
        .size:           2
        .value_kind:     hidden_remainder_x
      - .offset:         212
        .size:           2
        .value_kind:     hidden_remainder_y
      - .offset:         214
        .size:           2
        .value_kind:     hidden_remainder_z
      - .offset:         232
        .size:           8
        .value_kind:     hidden_global_offset_x
      - .offset:         240
        .size:           8
        .value_kind:     hidden_global_offset_y
      - .offset:         248
        .size:           8
        .value_kind:     hidden_global_offset_z
      - .offset:         256
        .size:           2
        .value_kind:     hidden_grid_dims
      - .offset:         312
        .size:           4
        .value_kind:     hidden_dynamic_lds_size
    .group_segment_fixed_size: 0
    .kernarg_segment_align: 8
    .kernarg_segment_size: 448
    .language:       OpenCL C
    .language_version:
      - 2
      - 0
    .max_flat_workgroup_size: 512
    .name:           _Z3fwd4Args
    .private_segment_fixed_size: 0
    .sgpr_count:     108
    .sgpr_spill_count: 77
    .symbol:         _Z3fwd4Args.kd
    .uniform_work_group_size: 1
    .uses_dynamic_stack: false
    .vgpr_count:     255
    .vgpr_spill_count: 0
    .wavefront_size: 64
